# v15 + GEMM k-loops: removed the mid-iteration workgroup barrier between the two wave halves (it orders no LDS hazard: segment-2 reads buffer kt, segment-2 loader writes buffer kt+1)
# speedup vs baseline: 1.0143x; 1.0143x over previous
.LBB0_116:
	s_or_b64 exec, exec, s[48:49]
	s_and_saveexec_b64 s[40:41], s[46:47]
	s_xor_b64 s[48:49], exec, s[40:41]
	s_cbranch_execz .LBB0_121
	s_cmp_gt_u32 s61, 42
	s_cbranch_scc1 .LBB0_119
	s_add_i32 s40, s72, 0x10000
	s_and_b32 s40, s40, 0x10000
	v_add_u32_e32 v0, s40, v198
	s_waitcnt vmcnt(7)
	ds_write_b128 v0, v[144:147]
	s_waitcnt vmcnt(6)
	ds_write_b128 v0, v[148:151] offset:32768
	s_waitcnt vmcnt(5)
	ds_write_b128 v0, v[152:155] offset:8192
	s_waitcnt vmcnt(4)
	ds_write_b128 v0, v[156:159] offset:40960
	s_waitcnt vmcnt(3)
	ds_write_b128 v0, v[160:163] offset:16384
	s_waitcnt vmcnt(2)
	ds_write_b128 v0, v[164:167] offset:49152
	s_waitcnt vmcnt(1)
	ds_write_b128 v0, v[168:171] offset:24576
	s_waitcnt vmcnt(0)
	ds_write_b128 v0, v[172:175] offset:57344

.LBB0_354:
	s_or_b64 exec, exec, s[48:49]
	s_and_saveexec_b64 s[40:41], s[46:47]
	s_xor_b64 s[48:49], exec, s[40:41]
	s_cbranch_execz .LBB0_367
	s_cmpk_eq_i32 s20, 0x780
	s_cbranch_scc1 .LBB0_357
	s_andn2_b32 s40, 0x10000, s29
	v_add_u32_e32 v0, s40, v195
	s_waitcnt vmcnt(4)
	ds_write_b128 v0, v[144:147]
	s_waitcnt vmcnt(3)
	ds_write_b128 v0, v[152:155] offset:32768
	ds_write_b128 v0, v[148:151] offset:8192
	s_waitcnt vmcnt(2)
	ds_write_b128 v0, v[156:159] offset:40960
	ds_write_b128 v0, v[160:163] offset:16384
	s_waitcnt vmcnt(1)
	ds_write_b128 v0, v[164:167] offset:49152
	ds_write_b128 v0, v[168:171] offset:24576
	s_waitcnt vmcnt(0)
	ds_write_b128 v0, v[172:175] offset:57344

.LBB0_486:
	s_or_b64 exec, exec, s[48:49]
	s_and_saveexec_b64 s[48:49], s[44:45]
	s_xor_b64 s[48:49], exec, s[48:49]
	s_cbranch_execz .LBB0_491
	s_cmp_gt_u32 s65, 14
	s_cbranch_scc1 .LBB0_489
	s_add_i32 s50, s72, 0x10000
	s_and_b32 s50, s50, 0x10000
	v_add_u32_e32 v0, s50, v198
	s_waitcnt vmcnt(7)
	ds_write_b128 v0, v[144:147]
	s_waitcnt vmcnt(3)
	ds_write_b128 v0, v[152:155] offset:32768
	ds_write_b128 v0, v[148:151] offset:8192
	s_waitcnt vmcnt(2)
	ds_write_b128 v0, v[160:163] offset:40960
	ds_write_b128 v0, v[156:159] offset:16384
	s_waitcnt vmcnt(1)
	ds_write_b128 v0, v[164:167] offset:49152
	ds_write_b128 v0, v[168:171] offset:24576
	s_waitcnt vmcnt(0)
	ds_write_b128 v0, v[172:175] offset:57344

.LBB0_583:
	s_or_b64 exec, exec, s[30:31]
	s_and_saveexec_b64 s[30:31], s[44:45]
	s_xor_b64 s[30:31], exec, s[30:31]
	s_cbranch_execz .LBB0_588
	s_cmpk_eq_i32 s20, 0x780
	s_cbranch_scc1 .LBB0_586
	s_andn2_b32 s46, 0x10000, s27
	v_add_u32_e32 v0, s46, v201
	s_waitcnt vmcnt(7)
	ds_write_b128 v0, v[144:147]
	s_waitcnt vmcnt(3)
	ds_write_b128 v0, v[152:155] offset:32768
	ds_write_b128 v0, v[148:151] offset:8192
	s_waitcnt vmcnt(2)
	ds_write_b128 v0, v[160:163] offset:40960
	ds_write_b128 v0, v[156:159] offset:16384
	s_waitcnt vmcnt(1)
	ds_write_b128 v0, v[164:167] offset:49152
	ds_write_b128 v0, v[168:171] offset:24576
	s_waitcnt vmcnt(0)
	ds_write_b128 v0, v[172:175] offset:57344

.LBB0_605:
	s_or_b64 exec, exec, s[22:23]
	s_and_saveexec_b64 s[22:23], s[44:45]
	s_xor_b64 s[22:23], exec, s[22:23]
	s_cbranch_execz .LBB0_611
	s_add_i32 s56, s49, -1
	s_cmp_ge_u32 s56, s54
	s_cbranch_scc1 .LBB0_608
	s_add_i32 s56, s53, 0x10000
	s_and_b32 s56, s56, 0x10000
	v_add_u32_e32 v0, s56, v201
	s_waitcnt vmcnt(7)
	ds_write_b128 v0, v[144:147]
	s_waitcnt vmcnt(6)
	ds_write_b128 v0, v[148:151] offset:32768
	s_waitcnt vmcnt(5)
	ds_write_b128 v0, v[152:155] offset:8192
	s_waitcnt vmcnt(4)
	ds_write_b128 v0, v[156:159] offset:40960
	s_waitcnt vmcnt(3)
	ds_write_b128 v0, v[160:163] offset:16384
	s_waitcnt vmcnt(2)
	ds_write_b128 v0, v[164:167] offset:49152
	s_waitcnt vmcnt(1)
	ds_write_b128 v0, v[168:171] offset:24576
	s_waitcnt vmcnt(0)
	ds_write_b128 v0, v[172:175] offset:57344

.LBB0_721:
	s_or_b64 exec, exec, s[20:21]
	s_and_saveexec_b64 s[20:21], s[44:45]
	s_xor_b64 s[20:21], exec, s[20:21]
	s_cbranch_execz .LBB0_726
	s_cmpk_eq_i32 s22, 0x780
	s_cbranch_scc1 .LBB0_724
	s_andn2_b32 s48, 0x10000, s26
	v_add_u32_e32 v0, s48, v201
	s_waitcnt vmcnt(7)
	ds_write_b128 v0, v[144:147]
	s_waitcnt vmcnt(6)
	ds_write_b128 v0, v[148:151] offset:32768
	s_waitcnt vmcnt(5)
	ds_write_b128 v0, v[152:155] offset:8192
	s_waitcnt vmcnt(4)
	ds_write_b128 v0, v[156:159] offset:40960
	s_waitcnt vmcnt(3)
	ds_write_b128 v0, v[160:163] offset:16384
	s_waitcnt vmcnt(2)
	ds_write_b128 v0, v[164:167] offset:49152
	s_waitcnt vmcnt(1)
	ds_write_b128 v0, v[168:171] offset:24576
	s_waitcnt vmcnt(0)
	ds_write_b128 v0, v[172:175] offset:57344
